# c23: in-proj dt tile, wave column 0 runs only the 8 MFMAs of its real 16-column fragment per K half (padding fragments skipped)
# speedup vs baseline: 1.0153x; 1.0102x over previous
; #define LDSAS __attribute__((address_space(3)))
; #define G_ISSUE(kt, st) do { G_ISSUE1(kt, st, 0); G_ISSUE1(kt, st, 1); G_ISSUE1(kt, st, 2); G_ISSUE1(kt, st, 3); } while (0)
; template <bool LOWREG = false>
; __device__ __forceinline__ void gemm_core(const bf16_t* __restrict__ A, int lda, const bf16_t* __restrict__ Bt, int ldb, int K, f32x4 (&acc)[8][4], unsigned char* smem, int tid) {
;     asm volatile("" : "+v"(tid));
;     const int lane = tid & 63, w = __builtin_amdgcn_readfirstlane(tid >> 6), wm = w >> 2, wn = w & 3, idx = lane & 15, kq = lane >> 4;
;     unsigned offA[4], offB[4];
; #pragma unroll
;     for (int j = 0; j < 4; ++j) { const int row = (j * 8 + w) * 8 + (lane >> 3), c = (lane & 7) ^ ((row >> 1) & 7);
;         offA[j] = (unsigned)(row * lda + c * 8) * 2u; offB[j] = (unsigned)(row * ldb + c * 8) * 2u; }
; #pragma unroll
;     for (int mi = 0; mi < 8; ++mi)
; #pragma unroll
;         for (int ni = 0; ni < 4; ++ni) acc[mi][ni] = (f32x4){0.f, 0.f, 0.f, 0.f};
;     LDSAS unsigned char* lds = (LDSAS unsigned char*)smem;
;     ...
;     const int nk = K >> 6;
;     G_ISSUE(0, 0);
;     asm volatile("s_waitcnt vmcnt(0)" ::: "memory");
;     __syncthreads();
;     const int swz = (idx >> 1) & 7;
;     const int aoff = (wm * 128 + idx) * 128, boff = G_AB + (wn * 64 + idx) * 128;
; __device__ void gemm1_phase(const Params& p, int l, int hb, unsigned char* smem) {
;     ...
;     for (int t = blockIdx.x; t < NTILES; t += gridDim.x) {
;         const int grp = t / GRP, r = t % GRP, jx = NT * (r & 7) + (r >> 3), mt = grp * 8 + (jx & 7), nt = jx >> 3;
;         const int m0 = mt * 256, n0 = nt * 256;
;         f32x4 acc[8][4];
;         int tid = threadIdx.x;
;         gemm_core(H + (size_t)m0 * 1024, 1024, Wt + (size_t)n0 * 1024, 1024, 1024, acc, smem, tid);
.LBB0_254:
	s_mul_hi_i32 s9, s60, 0x78787879
	s_lshr_b32 s11, s9, 31
	s_ashr_i32 s9, s9, 7
	s_add_i32 s9, s9, s11
	s_mul_i32 s11, s9, 0x110
	s_sub_i32 s11, s60, s11
	s_and_b32 s12, s11, 7
	s_mul_i32 s12, s12, 34
	s_ashr_i32 s11, s11, 3
	s_add_i32 s12, s12, s11
	s_lshl_b32 s11, s12, 8
	s_lshl_b32 s9, s9, 11
	s_and_b32 s11, s11, 0x700
	s_or_b32 s56, s11, s9
	s_lshl_b32 s11, s12, 5
	s_ashr_i32 s57, s56, 31
	s_and_b32 s36, s11, 0xffffff00
	s_lshl_b64 s[16:17], s[56:57], 11
	s_add_u32 s18, s92, s16
	s_addc_u32 s19, s93, s17
	s_ashr_i32 s37, s36, 31
	s_lshl_b64 s[20:21], s[36:37], 11
	v_mov_b32_e32 v0, v210
	s_add_u32 s22, s94, s20
	s_addc_u32 s23, s95, s21
	v_readfirstlane_b32 s12, v0
	s_ashr_i32 s24, s12, 6
	s_and_b32 s101, s24, 3
	s_cmp_lg_u32 s101, 0
	s_cselect_b32 s101, 1, 2
	s_cmp_eq_u32 s36, 0x2100
	s_cselect_b32 s101, s101, 0
	v_bfe_u32 v2, v0, 3, 3
	v_lshl_or_b32 v3, s24, 3, v2
	v_lshrrev_b32_e32 v4, 1, v3
	v_xor_b32_e32 v4, v4, v0
	v_lshlrev_b32_e32 v4, 4, v4
	s_lshl_b32 s9, s24, 10
	v_and_b32_e32 v4, 0x70, v4
	s_add_i32 s9, s9, 0
	v_lshl_or_b32 v3, v3, 11, v4
	s_mov_b32 m0, s9
	v_add_u32_e32 v5, 0x20000, v3
	global_load_lds_dwordx4 v3, s[18:19]
	s_add_i32 m0, s9, 0x8000
	v_add_u32_e32 v6, 0x40000, v3
	global_load_lds_dwordx4 v3, s[22:23]
	s_add_i32 m0, s9, 0x2000
	v_add_u32_e32 v7, 0x60000, v3
	global_load_lds_dwordx4 v5, s[18:19]
	s_add_i32 m0, s9, 0xa000
	v_and_b32_e32 v1, 15, v0
	global_load_lds_dwordx4 v5, s[22:23]
	s_add_i32 m0, s9, 0x4000
	v_bfe_u32 v8, v0, 4, 2
	global_load_lds_dwordx4 v6, s[18:19]
	s_add_i32 m0, s9, 0xc000
	v_lshrrev_b32_e32 v3, 1, v0
	global_load_lds_dwordx4 v6, s[22:23]
	s_add_i32 m0, s9, 0x6000
	v_bfe_u32 v0, v0, 1, 3
	global_load_lds_dwordx4 v7, s[18:19]
	s_add_i32 m0, s9, 0xe000
	s_lshr_b32 s18, s12, 1
	global_load_lds_dwordx4 v7, s[22:23]
	s_and_b32 s18, s18, 0x1ffff80
	s_and_b32 s12, s12, 0xc0
	v_or_b32_e32 v5, s18, v1
	v_or_b32_e32 v1, s12, v1
	s_lshl_b32 s12, s24, 14
	s_add_u32 s16, s96, s16
	v_lshlrev_b32_e32 v149, 7, v5
	v_bitop3_b32 v0, v8, v0, 4 bitop3:0x36
	v_lshlrev_b32_e32 v5, 11, v2
	s_addc_u32 s17, s97, s17
	s_add_i32 s18, s12, 0x20000
	v_lshlrev_b32_e32 v147, 7, v1
	v_bitop3_b32 v1, v8, v3, 7 bitop3:0x78
	v_lshlrev_b32_e32 v146, 4, v0
	v_or3_b32 v80, s12, v5, v4
	v_or3_b32 v0, s18, v5, v4
	s_add_i32 s18, s12, 0x40000
	s_add_i32 s12, s12, 0x60000
	v_lshlrev_b32_e32 v148, 4, v1
	v_mov_b32_e32 v1, v81
	v_or3_b32 v2, s18, v5, v4
	v_mov_b32_e32 v3, v81
	v_or3_b32 v4, s12, v5, v4
	v_mov_b32_e32 v5, v81
	v_lshl_add_u64 v[130:131], s[16:17], 0, v[80:81]
	v_lshl_add_u64 v[132:133], s[16:17], 0, v[0:1]
	v_lshl_add_u64 v[134:135], s[16:17], 0, v[2:3]
	v_lshl_add_u64 v[136:137], s[16:17], 0, v[4:5]
	s_add_u32 s16, s64, s20
	s_waitcnt vmcnt(0)
	s_addc_u32 s17, s65, s21
	v_lshl_add_u64 v[140:141], s[16:17], 0, v[0:1]
	v_mov_b32_e32 v0, 0
	v_lshl_add_u64 v[138:139], s[16:17], 0, v[80:81]
	v_lshl_add_u64 v[142:143], s[16:17], 0, v[2:3]
	v_lshl_add_u64 v[144:145], s[16:17], 0, v[4:5]
	s_mov_b32 s12, 0
	s_mov_b64 s[38:39], 0
	v_mov_b32_e32 v1, v0
	v_mov_b32_e32 v2, v0
	v_mov_b32_e32 v3, v0
	v_mov_b32_e32 v4, v0
	v_mov_b32_e32 v5, v0
	v_mov_b32_e32 v6, v0
	v_mov_b32_e32 v7, v0
	v_mov_b32_e32 v8, v0
	v_mov_b32_e32 v9, v0
	s_waitcnt vmcnt(0)
	v_mov_b32_e32 v10, v0
	v_mov_b32_e32 v11, v0
	v_mov_b32_e32 v12, v0
	v_mov_b32_e32 v13, v0
	v_mov_b32_e32 v14, v0
	v_mov_b32_e32 v15, v0
	v_mov_b32_e32 v16, v0
	v_mov_b32_e32 v17, v0
	v_mov_b32_e32 v18, v0
	v_mov_b32_e32 v19, v0
	v_mov_b32_e32 v20, v0
	v_mov_b32_e32 v21, v0
	v_mov_b32_e32 v22, v0
	v_mov_b32_e32 v23, v0
	v_mov_b32_e32 v24, v0
	v_mov_b32_e32 v25, v0
	v_mov_b32_e32 v26, v0
	v_mov_b32_e32 v27, v0
	v_mov_b32_e32 v28, v0
	v_mov_b32_e32 v29, v0
	v_mov_b32_e32 v30, v0
	v_mov_b32_e32 v31, v0
	v_mov_b32_e32 v32, v0
	v_mov_b32_e32 v33, v0
	v_mov_b32_e32 v34, v0
	v_mov_b32_e32 v35, v0
	v_mov_b32_e32 v36, v0
	v_mov_b32_e32 v37, v0
	v_mov_b32_e32 v38, v0
	v_mov_b32_e32 v39, v0
	v_mov_b32_e32 v40, v0
	v_mov_b32_e32 v41, v0
	v_mov_b32_e32 v42, v0
	v_mov_b32_e32 v43, v0
	v_mov_b32_e32 v44, v0
	v_mov_b32_e32 v45, v0
	v_mov_b32_e32 v46, v0
	v_mov_b32_e32 v47, v0
	v_mov_b32_e32 v48, v0
	v_mov_b32_e32 v49, v0
	v_mov_b32_e32 v50, v0
	v_mov_b32_e32 v51, v0
	v_mov_b32_e32 v52, v0
	v_mov_b32_e32 v53, v0
	v_mov_b32_e32 v54, v0
	v_mov_b32_e32 v55, v0
	v_mov_b32_e32 v56, v0
	v_mov_b32_e32 v57, v0
	v_mov_b32_e32 v58, v0
	v_mov_b32_e32 v59, v0
	v_mov_b32_e32 v60, v0
	v_mov_b32_e32 v61, v0
	v_mov_b32_e32 v62, v0
	v_mov_b32_e32 v63, v0
	v_mov_b32_e32 v64, v0
	v_mov_b32_e32 v65, v0
	v_mov_b32_e32 v66, v0
	v_mov_b32_e32 v67, v0
	v_mov_b32_e32 v68, v0
	v_mov_b32_e32 v69, v0
	v_mov_b32_e32 v70, v0
	v_mov_b32_e32 v71, v0
	v_mov_b32_e32 v72, v0
	v_mov_b32_e32 v73, v0
	v_mov_b32_e32 v74, v0
	v_mov_b32_e32 v75, v0
	v_mov_b32_e32 v76, v0
	v_mov_b32_e32 v77, v0
	v_mov_b32_e32 v78, v0
	v_mov_b32_e32 v79, v0
	v_mov_b32_e32 v82, v0
	v_mov_b32_e32 v83, v0
	v_mov_b32_e32 v84, v0
	v_mov_b32_e32 v85, v0
	v_mov_b32_e32 v86, v0
	v_mov_b32_e32 v87, v0
	v_mov_b32_e32 v88, v0
	v_mov_b32_e32 v89, v0
	v_mov_b32_e32 v90, v0
	v_mov_b32_e32 v91, v0
	v_mov_b32_e32 v92, v0
	v_mov_b32_e32 v93, v0
	v_mov_b32_e32 v94, v0
	v_mov_b32_e32 v95, v0
	v_mov_b32_e32 v96, v0
	v_mov_b32_e32 v97, v0
	v_mov_b32_e32 v98, v0
	v_mov_b32_e32 v99, v0
	v_mov_b32_e32 v100, v0
	v_mov_b32_e32 v101, v0
	v_mov_b32_e32 v102, v0
	v_mov_b32_e32 v103, v0
	v_mov_b32_e32 v104, v0
	v_mov_b32_e32 v105, v0
	v_mov_b32_e32 v106, v0
	v_mov_b32_e32 v107, v0
	v_mov_b32_e32 v108, v0
	v_mov_b32_e32 v109, v0
	v_mov_b32_e32 v110, v0
	v_mov_b32_e32 v111, v0
	v_mov_b32_e32 v112, v0
	v_mov_b32_e32 v113, v0
	v_mov_b32_e32 v114, v0
	v_mov_b32_e32 v115, v0
	v_mov_b32_e32 v116, v0
	v_mov_b32_e32 v117, v0
	v_mov_b32_e32 v118, v0
	v_mov_b32_e32 v119, v0
	v_mov_b32_e32 v120, v0
	v_mov_b32_e32 v121, v0
	v_mov_b32_e32 v122, v0
	v_mov_b32_e32 v123, v0
	v_mov_b32_e32 v124, v0
	v_mov_b32_e32 v125, v0
	v_mov_b32_e32 v126, v0
	v_mov_b32_e32 v127, v0
	v_mov_b32_e32 v128, v0
	v_mov_b32_e32 v129, v0
	s_waitcnt lgkmcnt(0)
	s_barrier

; template <bool LOWREG = false>
; __device__ __forceinline__ void gemm_core(const bf16_t* __restrict__ A, int lda, const bf16_t* __restrict__ Bt, int ldb, int K, f32x4 (&acc)[8][4], unsigned char* smem, int tid) {
;     ...
;         for (int ks = 0; ks < 2; ++ks) {
;             bf16x8 bfr[4], af[8];
;             const int co = ((ks * 4 + kq) ^ swz) * 16;
; #pragma unroll
;             for (int ni = 0; ni < 4; ++ni) bfr[ni] = *(const bf16x8*)(sb + boff + ni * 2048 + co);
; #pragma unroll
;             for (int mi = 0; mi < 8; ++mi) af[mi] = *(const bf16x8*)(sb + aoff + mi * 2048 + co);
;             if (more) { G_ISSUE1(kt + 1, st ^ 1, ks * 2); G_ISSUE1(kt + 1, st ^ 1, ks * 2 + 1); }
;             __builtin_amdgcn_sched_barrier(0);
;             __builtin_amdgcn_s_setprio(1);
; #pragma unroll
;             for (int mi = 0; mi < 8; ++mi)
; #pragma unroll
;                 for (int ni = 0; ni < 4; ++ni) acc[mi][ni] = __builtin_amdgcn_mfma_f32_16x16x32_bf16(bfr[ni], af[mi], acc[mi][ni], 0, 0, 0);
;             __builtin_amdgcn_s_setprio(0);
;             __builtin_amdgcn_sched_barrier(0);
;         }
.Lg1_dtalt1:
	s_cmp_eq_u32 s101, 1
	s_cbranch_scc1 .Lg1_dtskip1
	s_waitcnt lgkmcnt(0)
	v_mfma_f32_16x16x32_bf16 v[126:129], v[150:153], v[166:169], v[126:129]
	v_mfma_f32_16x16x32_bf16 v[110:113], v[150:153], v[170:173], v[110:113]
	v_mfma_f32_16x16x32_bf16 v[94:97], v[150:153], v[174:177], v[94:97]
	v_mfma_f32_16x16x32_bf16 v[76:79], v[150:153], v[180:183], v[76:79]
	v_mfma_f32_16x16x32_bf16 v[60:63], v[150:153], v[184:187], v[60:63]
	v_mfma_f32_16x16x32_bf16 v[44:47], v[150:153], v[188:191], v[44:47]
	v_mfma_f32_16x16x32_bf16 v[28:31], v[150:153], v[192:195], v[28:31]
	v_mfma_f32_16x16x32_bf16 v[12:15], v[150:153], v[196:199], v[12:15]
	s_branch .Lg1_dtskip1

; template <bool LOWREG = false>
; __device__ __forceinline__ void gemm_core(const bf16_t* __restrict__ A, int lda, const bf16_t* __restrict__ Bt, int ldb, int K, f32x4 (&acc)[8][4], unsigned char* smem, int tid) {
;     ...
;         for (int ks = 0; ks < 2; ++ks) {
;             bf16x8 bfr[4], af[8];
;             const int co = ((ks * 4 + kq) ^ swz) * 16;
; #pragma unroll
;             for (int ni = 0; ni < 4; ++ni) bfr[ni] = *(const bf16x8*)(sb + boff + ni * 2048 + co);
; #pragma unroll
;             for (int mi = 0; mi < 8; ++mi) af[mi] = *(const bf16x8*)(sb + aoff + mi * 2048 + co);
;             if (more) { G_ISSUE1(kt + 1, st ^ 1, ks * 2); G_ISSUE1(kt + 1, st ^ 1, ks * 2 + 1); }
;             __builtin_amdgcn_sched_barrier(0);
;             __builtin_amdgcn_s_setprio(1);
; #pragma unroll
;             for (int mi = 0; mi < 8; ++mi)
; #pragma unroll
;                 for (int ni = 0; ni < 4; ++ni) acc[mi][ni] = __builtin_amdgcn_mfma_f32_16x16x32_bf16(bfr[ni], af[mi], acc[mi][ni], 0, 0, 0);
;             __builtin_amdgcn_s_setprio(0);
;             __builtin_amdgcn_sched_barrier(0);
;         }
.Lg1_dtalt3:
	s_cmp_eq_u32 s101, 1
	s_cbranch_scc1 .Lg1_dtskip3
	s_waitcnt lgkmcnt(0)
	v_mfma_f32_16x16x32_bf16 v[126:129], v[180:183], v[162:165], v[126:129]
	v_mfma_f32_16x16x32_bf16 v[110:113], v[180:183], v[158:161], v[110:113]
	v_mfma_f32_16x16x32_bf16 v[94:97], v[180:183], v[154:157], v[94:97]
	v_mfma_f32_16x16x32_bf16 v[76:79], v[180:183], v[150:153], v[76:79]
	v_mfma_f32_16x16x32_bf16 v[60:63], v[180:183], v[142:145], v[60:63]
	v_mfma_f32_16x16x32_bf16 v[44:47], v[180:183], v[138:141], v[44:47]
	v_mfma_f32_16x16x32_bf16 v[28:31], v[180:183], v[134:137], v[28:31]
	v_mfma_f32_16x16x32_bf16 v[12:15], v[180:183], v[130:133], v[12:15]
	s_branch .Lg1_dtskip3
.Lg1_dtalt4:
	s_cmp_eq_u32 s101, 1
	s_cbranch_scc1 .Lg1_dtskip4
	s_waitcnt lgkmcnt(0)
	v_mfma_f32_16x16x32_bf16 v[126:129], v[180:183], v[160:163], v[126:129]
	v_mfma_f32_16x16x32_bf16 v[110:113], v[180:183], v[156:159], v[110:113]
	v_mfma_f32_16x16x32_bf16 v[94:97], v[180:183], v[152:155], v[94:97]
	v_mfma_f32_16x16x32_bf16 v[76:79], v[180:183], v[148:151], v[76:79]
	v_mfma_f32_16x16x32_bf16 v[60:63], v[180:183], v[142:145], v[60:63]
	v_mfma_f32_16x16x32_bf16 v[44:47], v[180:183], v[138:141], v[44:47]
	v_mfma_f32_16x16x32_bf16 v[28:31], v[180:183], v[134:137], v[28:31]
	v_mfma_f32_16x16x32_bf16 v[12:15], v[180:183], v[130:133], v[12:15]
	s_branch .Lg1_dtskip4
